# attention: reuse the item header's gcount value instead of reloading it per task
# baseline (speedup 1.0000x reference)
; DI void phase4(const Params& P, char* smem) {
;     ...
;     int lo = 0, hi = 1024;
;     while (hi - lo > 1) { const int mid = (lo + hi) >> 1; if (pre[mid] <= it) lo = mid; else hi = mid; }
;     const int bh = lo >> 5, n = lo & 31, b = bh >> 3, h = bh & 7;
;     const int ntask = 4 + ((gcount[lo] + 31) >> 5);
;     const int task = (it - pre[lo]) * 8 + wid;
;     uint4 kr[8], vr[8];
; #pragma unroll
;     for (int i = 0; i < 8; ++i) {
;       const int q = i * 256 + tid;
;       kr[i] = *reinterpret_cast<const uint4*>(Kb + ((long)(b * 8192 + n * 256 + (q >> 3))) * 512 + h * 64 + (q & 7) * 8);
;       vr[i] = *reinterpret_cast<const uint4*>(Vt + ((long)(bh * 64 + (q >> 5))) * 8192 + n * 256 + (q & 31) * 8);
;     }
; #pragma unroll
;     for (int i = 0; i < 8; ++i) {
;       const int q = i * 256 + tid, row = q >> 3;
;       *reinterpret_cast<uint4*>(Ks + row * 128 + (((q & 7) ^ ((row >> 1) & 7)) * 16)) = kr[i];
;       *reinterpret_cast<uint4*>(Vs + (q >> 5) * 528 + (q & 31) * 16) = vr[i];
;     }
;     __syncthreads();
;     if (act && task < ntask) {
.LBB0_769:
	v_add_u32_e32 v2, v0, v66
	v_ashrrev_i32_e32 v2, 1, v2
	v_lshl_add_u32 v3, v2, 2, v92
	ds_read_b32 v3, v3
	s_waitcnt lgkmcnt(0)
	v_cmp_gt_i32_e32 vcc, v3, v144
	s_nop 1
	v_cndmask_b32_e32 v0, v0, v2, vcc
	v_cndmask_b32_e32 v66, v2, v66, vcc
	v_sub_u32_e32 v2, v0, v66
	v_cmp_gt_i32_e32 vcc, 2, v2
	s_or_b64 s[0:1], vcc, s[0:1]
	s_andn2_b64 exec, exec, s[0:1]
	s_cbranch_execnz .LBB0_769
	s_or_b64 exec, exec, s[0:1]
	v_lshlrev_b32_e32 v0, 5, v66
	v_ashrrev_i32_e32 v74, 5, v66
	v_and_b32_e32 v16, 0xffffe000, v0
	v_lshlrev_b32_e32 v0, 8, v66
	v_and_b32_e32 v145, 0x1f00, v0
	v_lshlrev_b32_e32 v17, 6, v74
	v_lshlrev_b32_e32 v0, 7, v74
	v_and_b32_e32 v0, 0x380, v0
	v_or_b32_e32 v12, v17, v102
	v_lshl_add_u64 v[2:3], v[80:81], 0, v[0:1]
	v_lshlrev_b32_e32 v0, 1, v145
	v_ashrrev_i32_e32 v13, 31, v12
	v_lshl_add_u64 v[4:5], v[82:83], 0, v[0:1]
	v_lshlrev_b64 v[12:13], 14, v[12:13]
	v_lshl_add_u64 v[14:15], v[4:5], 0, v[12:13]
	v_or3_b32 v12, v16, v103, v145
	v_ashrrev_i32_e32 v13, 31, v12
	v_lshlrev_b64 v[12:13], 10, v[12:13]
	v_lshl_add_u64 v[18:19], v[2:3], 0, v[12:13]
	v_or_b32_e32 v12, v17, v104
	v_ashrrev_i32_e32 v13, 31, v12
	v_lshlrev_b64 v[12:13], 14, v[12:13]
	v_lshl_add_u64 v[22:23], v[4:5], 0, v[12:13]
	v_or3_b32 v12, v16, v105, v145
	v_ashrrev_i32_e32 v13, 31, v12
	v_lshlrev_b64 v[12:13], 10, v[12:13]
	v_lshl_add_u64 v[26:27], v[2:3], 0, v[12:13]
	v_or_b32_e32 v12, v17, v106
	v_ashrrev_i32_e32 v13, 31, v12
	v_lshlrev_b64 v[12:13], 14, v[12:13]
	v_lshl_add_u64 v[30:31], v[4:5], 0, v[12:13]
	v_or3_b32 v12, v16, v107, v145
	v_ashrrev_i32_e32 v13, 31, v12
	v_lshlrev_b64 v[12:13], 10, v[12:13]
	v_lshl_add_u64 v[34:35], v[2:3], 0, v[12:13]
	v_or_b32_e32 v12, v17, v108
	v_ashrrev_i32_e32 v13, 31, v12
	v_lshlrev_b64 v[12:13], 14, v[12:13]
	v_lshl_add_u64 v[38:39], v[4:5], 0, v[12:13]
	v_or3_b32 v12, v16, v109, v145
	v_ashrrev_i32_e32 v13, 31, v12
	v_lshlrev_b64 v[12:13], 10, v[12:13]
	v_lshl_add_u64 v[42:43], v[2:3], 0, v[12:13]
	v_or_b32_e32 v12, v17, v110
	v_ashrrev_i32_e32 v13, 31, v12
	v_lshlrev_b64 v[12:13], 14, v[12:13]
	v_lshl_add_u64 v[46:47], v[4:5], 0, v[12:13]
	v_or3_b32 v12, v16, v111, v145
	v_ashrrev_i32_e32 v13, 31, v12
	v_lshlrev_b64 v[12:13], 10, v[12:13]
	v_lshl_add_u64 v[50:51], v[2:3], 0, v[12:13]
	v_or_b32_e32 v12, v17, v112
	v_ashrrev_i32_e32 v13, 31, v12
	v_lshlrev_b64 v[12:13], 14, v[12:13]
	v_ashrrev_i32_e32 v67, 31, v66
	v_or3_b32 v6, v16, v175, v145
	v_or3_b32 v10, v16, v101, v145
	v_lshl_add_u64 v[54:55], v[4:5], 0, v[12:13]
	v_or3_b32 v12, v16, v113, v145
	v_lshl_add_u64 v[68:69], v[66:67], 2, s[28:29]
	v_ashrrev_i32_e32 v7, 31, v6
	v_ashrrev_i32_e32 v11, 31, v10
	v_ashrrev_i32_e32 v13, 31, v12
	global_load_dword v70, v[68:69], off
	v_lshlrev_b64 v[6:7], 10, v[6:7]
	v_lshlrev_b64 v[10:11], 10, v[10:11]
	v_lshlrev_b64 v[12:13], 10, v[12:13]
	v_lshl_add_u64 v[6:7], v[2:3], 0, v[6:7]
	v_or_b32_e32 v8, v17, v100
	v_lshl_add_u64 v[10:11], v[2:3], 0, v[10:11]
	v_lshl_add_u64 v[58:59], v[2:3], 0, v[12:13]
	v_or_b32_e32 v2, v17, v114
	v_ashrrev_i32_e32 v9, 31, v8
	v_ashrrev_i32_e32 v3, 31, v2
	v_lshlrev_b64 v[8:9], 14, v[8:9]
	v_lshlrev_b64 v[2:3], 14, v[2:3]
	v_lshl_add_u64 v[8:9], v[4:5], 0, v[8:9]
	v_lshl_add_u64 v[62:63], v[4:5], 0, v[2:3]
	global_load_dwordx4 v[2:5], v[6:7], off
	s_nop 0
	global_load_dwordx4 v[6:9], v[8:9], off
	s_nop 0
	global_load_dwordx4 v[10:13], v[10:11], off
	s_nop 0
	global_load_dwordx4 v[14:17], v[14:15], off
	s_nop 0
	global_load_dwordx4 v[18:21], v[18:19], off
	s_nop 0
	global_load_dwordx4 v[22:25], v[22:23], off
	s_nop 0
	global_load_dwordx4 v[26:29], v[26:27], off
	s_nop 0
	global_load_dwordx4 v[30:33], v[30:31], off
	s_nop 0
	global_load_dwordx4 v[34:37], v[34:35], off
	s_nop 0
	global_load_dwordx4 v[38:41], v[38:39], off
	s_nop 0
	global_load_dwordx4 v[42:45], v[42:43], off
	s_nop 0
	global_load_dwordx4 v[46:49], v[46:47], off
	s_nop 0
	global_load_dwordx4 v[50:53], v[50:51], off
	s_nop 0
	global_load_dwordx4 v[54:57], v[54:55], off
	s_nop 0
	global_load_dwordx4 v[58:61], v[58:59], off
	s_nop 0
	global_load_dwordx4 v[62:65], v[62:63], off
	v_lshl_add_u32 v0, v66, 2, v92
	ds_read_b32 v146, v0
	s_waitcnt vmcnt(15)
	ds_write_b128 v115, v[2:5]
	s_waitcnt vmcnt(14)
	ds_write_b128 v116, v[6:9]
	s_waitcnt vmcnt(13)
	ds_write_b128 v117, v[10:13]
	s_waitcnt vmcnt(12)
	ds_write_b128 v118, v[14:17]
	s_waitcnt vmcnt(11)
	ds_write_b128 v119, v[18:21]
	s_waitcnt vmcnt(10)
	ds_write_b128 v120, v[22:25]
	s_waitcnt vmcnt(9)
	ds_write_b128 v121, v[26:29]
	s_waitcnt vmcnt(8)
	ds_write_b128 v122, v[30:33]
	s_waitcnt vmcnt(7)
	ds_write_b128 v123, v[34:37]
	s_waitcnt vmcnt(6)
	ds_write_b128 v125, v[38:41]
	s_waitcnt vmcnt(5)
	ds_write_b128 v126, v[42:45]
	s_waitcnt vmcnt(4)
	ds_write_b128 v127, v[46:49]
	s_waitcnt vmcnt(3)
	ds_write_b128 v130, v[50:53]
	s_waitcnt vmcnt(2)
	ds_write_b128 v131, v[54:57]
	s_waitcnt vmcnt(1)
	ds_write_b128 v132, v[58:61]
	s_waitcnt vmcnt(0)
	ds_write_b128 v133, v[62:65]
	v_add_u32_e32 v0, 31, v70
	v_mov_b32_e32 v212, v70
	v_ashrrev_i32_e32 v77, 5, v0
	s_waitcnt lgkmcnt(14)
	v_sub_u32_e32 v76, v144, v146
	v_add_u32_e32 v0, 4, v77
	v_lshl_or_b32 v75, v76, 3, v194
	v_cmp_lt_i32_e32 vcc, v75, v0
	s_and_b64 s[0:1], s[6:7], vcc
	s_waitcnt lgkmcnt(0)
	s_barrier
	s_and_saveexec_b64 s[48:49], s[0:1]
	s_cbranch_execz .LBB0_775
	v_cmp_lt_i32_e32 vcc, 3, v75
	s_mov_b64 s[50:51], 0
	s_and_saveexec_b64 s[0:1], vcc
	s_xor_b64 s[24:25], exec, s[0:1]
	s_cbranch_execnz .LBB0_785
	s_andn2_saveexec_b64 s[56:57], s[24:25]
	s_cbranch_execnz .LBB0_801

; DI void attn_task(const Params& P, int bh, int n, int t, int lane, const char* Ks, const char* Vs) {
;     ...
;     const int cnt = gcount[bh * 32 + n], idx = (t - 8) * 32 + r;
;     valid = idx < cnt;
;     const int e = list[((long)(bh * 32 + n)) * 8192 + (valid ? idx : 0)];
;     lq = e >> 2; slot = e & 3;
; DI void phase4(const Params& P, char* smem) {
;     ...
;     if (act && task + 4 < ntask) attn_task(P, bh, n, task + 4 - 4 + 8, lane, Ks, Vs);
.LBB0_775:
	s_or_b64 exec, exec, s[48:49]
	v_cmp_lt_i32_e32 vcc, v75, v77
	s_and_b64 s[0:1], s[6:7], vcc
	s_and_saveexec_b64 s[20:21], s[0:1]
	s_cbranch_execz .LBB0_767
	v_add_u32_e32 v0, 8, v75
	v_cmp_lt_i32_e32 vcc, -1, v76
	s_and_saveexec_b64 s[0:1], vcc
	s_xor_b64 s[0:1], exec, s[0:1]
	s_cbranch_execz .LBB0_778
	v_mov_b32_e32 v4, v212
	v_lshl_add_u32 v0, v0, 5, v98
	v_lshlrev_b64 v[2:3], 14, v[66:67]
	v_lshl_add_u64 v[2:3], s[30:31], 0, v[2:3]
	v_cmp_lt_i32_e64 s[24:25], v0, v4
	s_nop 1
	v_cndmask_b32_e64 v0, 0, v0, s[24:25]
	v_lshl_add_u64 v[2:3], v[0:1], 1, v[2:3]
	global_load_ushort v0, v[2:3], off
	s_waitcnt vmcnt(0)
	v_lshrrev_b32_e32 v148, 2, v0
	v_and_b32_e32 v88, 3, v0

; DI void attn_task(const Params& P, int bh, int n, int t, int lane, const char* Ks, const char* Vs) {
;     ...
;     const int cnt = gcount[bh * 32 + n], idx = (t - 8) * 32 + r;
;     valid = idx < cnt;
;     const int e = list[((long)(bh * 32 + n)) * 8192 + (valid ? idx : 0)];
;     lq = e >> 2; slot = e & 3;
; DI void phase4(const Params& P, char* smem) {
;     ...
;       else attn_task(P, bh, n, task - 4 + 8, lane, Ks, Vs);
.LBB0_785:
	v_or_b32_e32 v0, 4, v75
	v_cmp_ne_u32_e32 vcc, v144, v146
	s_and_saveexec_b64 s[0:1], vcc
	s_xor_b64 s[0:1], exec, s[0:1]
	s_cbranch_execz .LBB0_787
	v_mov_b32_e32 v4, v212
	v_lshl_add_u32 v0, v0, 5, v98
	v_lshlrev_b64 v[2:3], 14, v[66:67]
	v_lshl_add_u64 v[2:3], s[30:31], 0, v[2:3]
	v_cmp_lt_i32_e64 s[50:51], v0, v4
	s_nop 1
	v_cndmask_b32_e64 v0, 0, v0, s[50:51]
	v_lshl_add_u64 v[2:3], v[0:1], 1, v[2:3]
	global_load_ushort v0, v[2:3], off
	s_waitcnt vmcnt(0)
	v_lshrrev_b32_e32 v78, 2, v0
	v_and_b32_e32 v70, 3, v0

; DI void attn_task(const Params& P, int bh, int n, int t, int lane, const char* Ks, const char* Vs) {
;     ...
;     const int cnt = gcount[bh * 32 + n], idx = (t - 8) * 32 + r;
;     valid = idx < cnt;
;     const int e = list[((long)(bh * 32 + n)) * 8192 + (valid ? idx : 0)];
;     lq = e >> 2; slot = e & 3;
; DI void phase4(const Params& P, char* smem) {
;     ...
;       if (task < 4) { attn_task(P, bh, n, task, lane, Ks, Vs); attn_task(P, bh, n, 7 - task, lane, Ks, Vs); }
.LBB0_809:
	s_or_b64 exec, exec, s[0:1]
	v_sub_u32_e32 v2, 7, v75
	v_cmp_gt_i32_e32 vcc, 0, v76
	s_and_saveexec_b64 s[0:1], vcc
	s_xor_b64 s[0:1], exec, s[0:1]
	s_cbranch_execz .LBB0_811
	v_mov_b32_e32 v6, v212
	v_lshl_add_u32 v2, v2, 5, v98
	v_lshlrev_b64 v[4:5], 14, v[66:67]
	v_mov_b32_e32 v3, v1
	v_lshl_add_u64 v[4:5], s[30:31], 0, v[4:5]
	v_cmp_lt_i32_e64 s[24:25], v2, v6
	s_nop 1
	v_cndmask_b32_e64 v2, 0, v2, s[24:25]
	v_lshl_add_u64 v[2:3], v[2:3], 1, v[4:5]
	global_load_ushort v2, v[2:3], off
	s_waitcnt vmcnt(0)
	v_lshrrev_b32_e32 v79, 2, v2
	v_and_b32_e32 v70, 3, v2
